# v12 with the grid barrier's non-leader workgroups polling the cross-XCD release generation directly (no per-XCD relay round trip)
# baseline (speedup 1.0000x reference)
.LBB0_41:
	s_or_b64 exec, exec, s[4:5]
	v_cvt_f32_u32_e32 v4, v2
	s_waitcnt vmcnt(0)
	v_readfirstlane_b32 s0, v3
	v_sub_u32_e32 v3, 0, v2
	v_rcp_iflag_f32_e32 v4, v4
	v_add_u32_e32 v5, s0, v1
	v_mul_f32_e32 v4, 0x4f7ffffe, v4
	v_cvt_u32_f32_e32 v4, v4
	v_mul_lo_u32 v1, v3, v4
	v_mul_hi_u32 v1, v4, v1
	v_add_u32_e32 v1, v4, v1
	v_mul_hi_u32 v1, v5, v1
	v_mul_lo_u32 v3, v1, v2
	v_sub_u32_e32 v3, v5, v3
	v_add_u32_e32 v4, 1, v1
	v_cmp_ge_u32_e32 vcc, v3, v2
	s_nop 1
	v_cndmask_b32_e32 v1, v1, v4, vcc
	v_sub_u32_e32 v4, v3, v2
	v_cndmask_b32_e32 v3, v3, v4, vcc
	v_add_u32_e32 v4, 1, v1
	v_cmp_ge_u32_e32 vcc, v3, v2
	v_add_u32_e32 v3, 1, v5
	s_nop 0
	v_cndmask_b32_e32 v1, v1, v4, vcc
	v_mul_lo_u32 v4, v2, v1
	v_add_u32_e32 v2, v4, v2
	v_cmp_ne_u32_e32 vcc, v3, v2
	s_and_saveexec_b64 s[0:1], vcc
	s_xor_b64 s[4:5], exec, s[0:1]
	s_cbranch_execz .LBB0_55
	v_readlane_b32 s0, v253, 43
	v_readlane_b32 s1, v253, 44
	s_waitcnt lgkmcnt(0)
	s_nop 3
	global_load_dword v0, v157, s[0:1] sc1
	s_waitcnt vmcnt(0)
	v_cmp_eq_u32_e32 vcc, v0, v1
	s_and_saveexec_b64 s[6:7], vcc
	s_cbranch_execz .LBB0_54
	s_mov_b32 s0, 1
	s_mov_b64 s[12:13], 0
	s_branch .LBB0_45

.LBB0_47:
	v_readlane_b32 s18, v253, 43
	v_readlane_b32 s19, v253, 44
	s_add_i32 s0, s0, 1
	s_mov_b64 s[22:23], -1
	s_nop 2
	global_load_dword v0, v157, s[18:19] sc1
	s_waitcnt vmcnt(0)
	v_cmp_ne_u32_e32 vcc, v0, v1
	s_orn2_b64 s[20:21], vcc, exec
	s_branch .LBB0_44
